# MLA rotated loop: boundary block issues its PV MFMAs first so the post-barrier K-fragment reads land under them; redundant per-tile address code dropped
# speedup vs baseline: 1.0139x; 1.0139x over previous
.LBB0_481:
	s_waitcnt lgkmcnt(13)
	v_mfma_f32_32x32x16_bf16 v[112:127], v[144:147], v[184:187], v[64:79]
	v_exp_f32_e32 v80, v80
	v_exp_f32_e32 v81, v81
	v_add_f32_e32 v244, v244, v80
	v_add_f32_e32 v244, v244, v81
	v_cvt_pk_bf16_f32 v80, v80, v81
	v_mfma_f32_32x32x16_bf16 v[128:143], v[144:147], v[200:203], v[64:79]
	ds_read_b128 v[144:147], v242 offset:12288
	v_exp_f32_e32 v82, v82
	v_exp_f32_e32 v83, v83
	v_add_f32_e32 v244, v244, v82
	v_add_f32_e32 v244, v244, v83
	v_cvt_pk_bf16_f32 v81, v82, v83
	s_waitcnt lgkmcnt(13)
	v_mfma_f32_32x32x16_bf16 v[112:127], v[148:151], v[188:191], v[112:127]
	v_exp_f32_e32 v84, v84
	v_exp_f32_e32 v85, v85
	v_add_f32_e32 v244, v244, v84
	v_add_f32_e32 v244, v244, v85
	v_cvt_pk_bf16_f32 v82, v84, v85
	v_mfma_f32_32x32x16_bf16 v[128:143], v[148:151], v[204:207], v[128:143]
	ds_read_b128 v[148:151], v242 offset:13312
	v_exp_f32_e32 v86, v86
	v_exp_f32_e32 v87, v87
	v_add_f32_e32 v244, v244, v86
	v_add_f32_e32 v244, v244, v87
	s_waitcnt lgkmcnt(13)
	v_mfma_f32_32x32x16_bf16 v[112:127], v[152:155], v[192:195], v[112:127]
	v_cvt_pk_bf16_f32 v83, v86, v87
	v_exp_f32_e32 v96, v96
	v_exp_f32_e32 v97, v97
	v_add_f32_e32 v245, v245, v96
	v_mfma_f32_32x32x16_bf16 v[128:143], v[152:155], v[208:211], v[128:143]
	ds_read_b128 v[152:155], v242 offset:14336
	v_add_f32_e32 v245, v245, v97
	v_cvt_pk_bf16_f32 v96, v96, v97
	v_exp_f32_e32 v98, v98
	v_exp_f32_e32 v99, v99
	s_waitcnt lgkmcnt(9)
	v_mfma_f32_32x32x16_bf16 v[48:63], v[80:83], v[168:171], v[48:63]
	v_add_f32_e32 v245, v245, v98
	v_add_f32_e32 v245, v245, v99
	v_cvt_pk_bf16_f32 v97, v98, v99
	v_exp_f32_e32 v100, v100
	v_exp_f32_e32 v101, v101
	v_mfma_f32_32x32x16_bf16 v[112:127], v[156:159], v[196:199], v[112:127]
	v_add_f32_e32 v245, v245, v100
	v_add_f32_e32 v245, v245, v101
	v_cvt_pk_bf16_f32 v98, v100, v101
	v_exp_f32_e32 v102, v102
	v_exp_f32_e32 v103, v103
	s_waitcnt lgkmcnt(7)
	v_mfma_f32_32x32x16_bf16 v[32:47], v[80:83], v[176:179], v[32:47]
	v_add_f32_e32 v245, v245, v102
	v_add_f32_e32 v245, v245, v103
	v_cvt_pk_bf16_f32 v99, v102, v103
	v_exp_f32_e32 v88, v88
	v_mfma_f32_32x32x16_bf16 v[128:143], v[156:159], v[212:215], v[128:143]
	ds_read_b128 v[156:159], v242 offset:15360
	v_exp_f32_e32 v89, v89
	v_add_f32_e32 v244, v244, v88
	v_add_f32_e32 v244, v244, v89
	v_cvt_pk_bf16_f32 v88, v88, v89
	v_mfma_f32_32x32x16_bf16 v[112:127], v[160:163], v[216:219], v[112:127]
	v_exp_f32_e32 v90, v90
	v_exp_f32_e32 v91, v91
	v_add_f32_e32 v244, v244, v90
	v_add_f32_e32 v244, v244, v91
	v_cvt_pk_bf16_f32 v89, v90, v91
	v_mfma_f32_32x32x16_bf16 v[128:143], v[160:163], v[224:227], v[128:143]
	ds_read_b128 v[160:163], v242 offset:16384
	v_exp_f32_e32 v92, v92
	v_exp_f32_e32 v93, v93
	v_add_f32_e32 v244, v244, v92
	v_add_f32_e32 v244, v244, v93
	v_cvt_pk_bf16_f32 v90, v92, v93
	v_mfma_f32_32x32x16_bf16 v[16:31], v[96:99], v[168:171], v[16:31]
	v_exp_f32_e32 v94, v94
	v_exp_f32_e32 v95, v95
	v_add_f32_e32 v244, v244, v94
	v_add_f32_e32 v244, v244, v95
	v_mfma_f32_32x32x16_bf16 v[112:127], v[164:167], v[220:223], v[112:127]
	v_cvt_pk_bf16_f32 v91, v94, v95
	v_exp_f32_e32 v104, v104
	v_exp_f32_e32 v105, v105
	v_add_f32_e32 v245, v245, v104
	v_mfma_f32_32x32x16_bf16 v[0:15], v[96:99], v[176:179], v[0:15]
	v_add_f32_e32 v245, v245, v105
	v_cvt_pk_bf16_f32 v104, v104, v105
	v_exp_f32_e32 v106, v106
	v_exp_f32_e32 v107, v107
	v_add_f32_e32 v245, v245, v106
	v_mfma_f32_32x32x16_bf16 v[128:143], v[164:167], v[228:231], v[128:143]
	ds_read_b128 v[164:167], v242 offset:17408
	v_add_f32_e32 v245, v245, v107
	v_cvt_pk_bf16_f32 v105, v106, v107
	v_exp_f32_e32 v108, v108
	v_exp_f32_e32 v109, v109
	v_add_f32_e32 v245, v245, v108
	s_waitcnt lgkmcnt(8)
	v_mfma_f32_32x32x16_bf16 v[48:63], v[88:91], v[172:175], v[48:63]
	v_add_f32_e32 v245, v245, v109
	v_cvt_pk_bf16_f32 v106, v108, v109
	v_exp_f32_e32 v110, v110
	v_exp_f32_e32 v111, v111
	s_waitcnt lgkmcnt(6)
	v_mfma_f32_32x32x16_bf16 v[32:47], v[88:91], v[180:183], v[32:47]
	v_add_f32_e32 v245, v245, v110
	v_add_f32_e32 v245, v245, v111
	v_cvt_pk_bf16_f32 v107, v110, v111
	ds_read_b64_tr_b16 v[168:169], v241 offset:53248
	ds_read_b64_tr_b16 v[170:171], v241 offset:54272
	ds_read_b64_tr_b16 v[176:177], v232 offset:53248
	ds_read_b64_tr_b16 v[178:179], v232 offset:54272
	v_mfma_f32_32x32x16_bf16 v[16:31], v[104:107], v[172:175], v[16:31]
	ds_read_b64_tr_b16 v[172:173], v241 offset:55296
	ds_read_b64_tr_b16 v[174:175], v241 offset:56320
	v_mfma_f32_32x32x16_bf16 v[0:15], v[104:107], v[180:183], v[0:15]
	ds_read_b64_tr_b16 v[180:181], v232 offset:55296
	ds_read_b64_tr_b16 v[182:183], v232 offset:56320
	s_waitcnt lgkmcnt(13)
	v_mfma_f32_32x32x16_bf16 v[80:95], v[144:147], v[184:187], v[64:79]
	v_exp_f32_e32 v112, v112
	v_exp_f32_e32 v113, v113
	v_add_f32_e32 v244, v244, v112
	v_add_f32_e32 v244, v244, v113
	v_cvt_pk_bf16_f32 v112, v112, v113
	v_mfma_f32_32x32x16_bf16 v[96:111], v[144:147], v[200:203], v[64:79]
	ds_read_b128 v[144:147], v242 offset:18432
	v_exp_f32_e32 v114, v114
	v_exp_f32_e32 v115, v115
	v_add_f32_e32 v244, v244, v114
	v_add_f32_e32 v244, v244, v115
	v_cvt_pk_bf16_f32 v113, v114, v115
	s_waitcnt lgkmcnt(13)
	v_mfma_f32_32x32x16_bf16 v[80:95], v[148:151], v[188:191], v[80:95]
	v_exp_f32_e32 v116, v116
	v_exp_f32_e32 v117, v117
	v_add_f32_e32 v244, v244, v116
	v_add_f32_e32 v244, v244, v117
	v_cvt_pk_bf16_f32 v114, v116, v117
	v_mfma_f32_32x32x16_bf16 v[96:111], v[148:151], v[204:207], v[96:111]
	ds_read_b128 v[148:151], v242 offset:19456
	v_exp_f32_e32 v118, v118
	v_exp_f32_e32 v119, v119
	v_add_f32_e32 v244, v244, v118
	v_add_f32_e32 v244, v244, v119
	s_waitcnt lgkmcnt(13)
	v_mfma_f32_32x32x16_bf16 v[80:95], v[152:155], v[192:195], v[80:95]
	v_cvt_pk_bf16_f32 v115, v118, v119
	v_exp_f32_e32 v128, v128
	v_exp_f32_e32 v129, v129
	v_add_f32_e32 v245, v245, v128
	v_mfma_f32_32x32x16_bf16 v[96:111], v[152:155], v[208:211], v[96:111]
	ds_read_b128 v[152:155], v242 offset:20480
	v_add_f32_e32 v245, v245, v129
	v_cvt_pk_bf16_f32 v128, v128, v129
	v_exp_f32_e32 v130, v130
	v_exp_f32_e32 v131, v131
	s_waitcnt lgkmcnt(9)
	v_mfma_f32_32x32x16_bf16 v[48:63], v[112:115], v[168:171], v[48:63]
	v_add_f32_e32 v245, v245, v130
	v_add_f32_e32 v245, v245, v131
	v_cvt_pk_bf16_f32 v129, v130, v131
	v_exp_f32_e32 v132, v132
	v_exp_f32_e32 v133, v133
	v_mfma_f32_32x32x16_bf16 v[80:95], v[156:159], v[196:199], v[80:95]
	v_add_f32_e32 v245, v245, v132
	v_add_f32_e32 v245, v245, v133
	v_cvt_pk_bf16_f32 v130, v132, v133
	v_exp_f32_e32 v134, v134
	v_exp_f32_e32 v135, v135
	s_waitcnt lgkmcnt(7)
	v_mfma_f32_32x32x16_bf16 v[32:47], v[112:115], v[176:179], v[32:47]
	v_add_f32_e32 v245, v245, v134
	v_add_f32_e32 v245, v245, v135
	v_cvt_pk_bf16_f32 v131, v134, v135
	v_exp_f32_e32 v120, v120
	v_mfma_f32_32x32x16_bf16 v[96:111], v[156:159], v[212:215], v[96:111]
	ds_read_b128 v[156:159], v242 offset:21504
	v_exp_f32_e32 v121, v121
	v_add_f32_e32 v244, v244, v120
	v_add_f32_e32 v244, v244, v121
	v_cvt_pk_bf16_f32 v120, v120, v121
	v_mfma_f32_32x32x16_bf16 v[80:95], v[160:163], v[216:219], v[80:95]
	v_exp_f32_e32 v122, v122
	v_exp_f32_e32 v123, v123
	v_add_f32_e32 v244, v244, v122
	v_add_f32_e32 v244, v244, v123
	v_cvt_pk_bf16_f32 v121, v122, v123
	v_mfma_f32_32x32x16_bf16 v[96:111], v[160:163], v[224:227], v[96:111]
	ds_read_b128 v[160:163], v242 offset:22528
	v_exp_f32_e32 v124, v124
	v_exp_f32_e32 v125, v125
	v_add_f32_e32 v244, v244, v124
	v_add_f32_e32 v244, v244, v125
	v_cvt_pk_bf16_f32 v122, v124, v125
	v_mfma_f32_32x32x16_bf16 v[16:31], v[128:131], v[168:171], v[16:31]
	v_exp_f32_e32 v126, v126
	v_exp_f32_e32 v127, v127
	v_add_f32_e32 v244, v244, v126
	v_add_f32_e32 v244, v244, v127
	v_mfma_f32_32x32x16_bf16 v[80:95], v[164:167], v[220:223], v[80:95]
	v_cvt_pk_bf16_f32 v123, v126, v127
	v_exp_f32_e32 v136, v136
	v_exp_f32_e32 v137, v137
	v_add_f32_e32 v245, v245, v136
	v_mfma_f32_32x32x16_bf16 v[0:15], v[128:131], v[176:179], v[0:15]
	v_add_f32_e32 v245, v245, v137
	v_cvt_pk_bf16_f32 v136, v136, v137
	v_exp_f32_e32 v138, v138
	v_exp_f32_e32 v139, v139
	v_add_f32_e32 v245, v245, v138
	v_mfma_f32_32x32x16_bf16 v[96:111], v[164:167], v[228:231], v[96:111]
	ds_read_b128 v[164:167], v242 offset:23552
	v_add_f32_e32 v245, v245, v139
	v_cvt_pk_bf16_f32 v137, v138, v139
	v_exp_f32_e32 v140, v140
	v_exp_f32_e32 v141, v141
	v_add_f32_e32 v245, v245, v140
	s_waitcnt lgkmcnt(8)
	v_mfma_f32_32x32x16_bf16 v[48:63], v[120:123], v[172:175], v[48:63]
	v_add_f32_e32 v245, v245, v141
	v_cvt_pk_bf16_f32 v138, v140, v141
	v_exp_f32_e32 v142, v142
	v_exp_f32_e32 v143, v143
	s_waitcnt lgkmcnt(6)
	v_mfma_f32_32x32x16_bf16 v[32:47], v[120:123], v[180:183], v[32:47]
	v_add_f32_e32 v245, v245, v142
	v_add_f32_e32 v245, v245, v143
	v_cvt_pk_bf16_f32 v139, v142, v143
	ds_read_b64_tr_b16 v[168:169], v241 offset:57344
	ds_read_b64_tr_b16 v[170:171], v241 offset:58368
	ds_read_b64_tr_b16 v[176:177], v232 offset:57344
	ds_read_b64_tr_b16 v[178:179], v232 offset:58368
	v_mfma_f32_32x32x16_bf16 v[16:31], v[136:139], v[172:175], v[16:31]
	ds_read_b64_tr_b16 v[172:173], v241 offset:59392
	ds_read_b64_tr_b16 v[174:175], v241 offset:60416
	v_mfma_f32_32x32x16_bf16 v[0:15], v[136:139], v[180:183], v[0:15]
	ds_read_b64_tr_b16 v[180:181], v232 offset:59392
	ds_read_b64_tr_b16 v[182:183], v232 offset:60416
	s_waitcnt lgkmcnt(13)
	v_mfma_f32_32x32x16_bf16 v[112:127], v[144:147], v[184:187], v[64:79]
	v_exp_f32_e32 v80, v80
	v_exp_f32_e32 v81, v81
	v_add_f32_e32 v244, v244, v80
	v_add_f32_e32 v244, v244, v81
	v_cvt_pk_bf16_f32 v80, v80, v81
	v_mfma_f32_32x32x16_bf16 v[128:143], v[144:147], v[200:203], v[64:79]
	v_exp_f32_e32 v82, v82
	v_exp_f32_e32 v83, v83
	v_add_f32_e32 v244, v244, v82
	v_add_f32_e32 v244, v244, v83
	v_cvt_pk_bf16_f32 v81, v82, v83
	s_waitcnt lgkmcnt(12)
	v_mfma_f32_32x32x16_bf16 v[112:127], v[148:151], v[188:191], v[112:127]
	v_exp_f32_e32 v84, v84
	v_exp_f32_e32 v85, v85
	v_add_f32_e32 v244, v244, v84
	v_add_f32_e32 v244, v244, v85
	v_cvt_pk_bf16_f32 v82, v84, v85
	v_mfma_f32_32x32x16_bf16 v[128:143], v[148:151], v[204:207], v[128:143]
	v_exp_f32_e32 v86, v86
	v_exp_f32_e32 v87, v87
	v_add_f32_e32 v244, v244, v86
	v_add_f32_e32 v244, v244, v87
	s_waitcnt lgkmcnt(11)
	v_mfma_f32_32x32x16_bf16 v[112:127], v[152:155], v[192:195], v[112:127]
	v_cvt_pk_bf16_f32 v83, v86, v87
	v_exp_f32_e32 v96, v96
	v_exp_f32_e32 v97, v97
	v_add_f32_e32 v245, v245, v96
	v_mfma_f32_32x32x16_bf16 v[128:143], v[152:155], v[208:211], v[128:143]
	v_add_f32_e32 v245, v245, v97
	v_cvt_pk_bf16_f32 v96, v96, v97
	v_exp_f32_e32 v98, v98
	v_exp_f32_e32 v99, v99
	s_waitcnt lgkmcnt(6)
	v_mfma_f32_32x32x16_bf16 v[48:63], v[80:83], v[168:171], v[48:63]
	v_add_f32_e32 v245, v245, v98
	v_add_f32_e32 v245, v245, v99
	v_cvt_pk_bf16_f32 v97, v98, v99
	v_exp_f32_e32 v100, v100
	v_exp_f32_e32 v101, v101
	v_mfma_f32_32x32x16_bf16 v[112:127], v[156:159], v[196:199], v[112:127]
	v_add_f32_e32 v245, v245, v100
	v_add_f32_e32 v245, v245, v101
	v_cvt_pk_bf16_f32 v98, v100, v101
	v_exp_f32_e32 v102, v102
	v_exp_f32_e32 v103, v103
	s_waitcnt lgkmcnt(4)
	v_mfma_f32_32x32x16_bf16 v[32:47], v[80:83], v[176:179], v[32:47]
	v_add_f32_e32 v245, v245, v102
	v_add_f32_e32 v245, v245, v103
	v_cvt_pk_bf16_f32 v99, v102, v103
	v_exp_f32_e32 v88, v88
	v_mfma_f32_32x32x16_bf16 v[128:143], v[156:159], v[212:215], v[128:143]
	v_exp_f32_e32 v89, v89
	v_add_f32_e32 v244, v244, v88
	v_add_f32_e32 v244, v244, v89
	v_cvt_pk_bf16_f32 v88, v88, v89
	v_mfma_f32_32x32x16_bf16 v[112:127], v[160:163], v[216:219], v[112:127]
	v_exp_f32_e32 v90, v90
	v_exp_f32_e32 v91, v91
	v_add_f32_e32 v244, v244, v90
	v_add_f32_e32 v244, v244, v91
	v_cvt_pk_bf16_f32 v89, v90, v91
	v_mfma_f32_32x32x16_bf16 v[128:143], v[160:163], v[224:227], v[128:143]
	v_exp_f32_e32 v92, v92
	v_exp_f32_e32 v93, v93
	v_add_f32_e32 v244, v244, v92
	v_add_f32_e32 v244, v244, v93
	v_cvt_pk_bf16_f32 v90, v92, v93
	v_mfma_f32_32x32x16_bf16 v[16:31], v[96:99], v[168:171], v[16:31]
	v_exp_f32_e32 v94, v94
	v_exp_f32_e32 v95, v95
	v_add_f32_e32 v244, v244, v94
	v_add_f32_e32 v244, v244, v95
	v_mfma_f32_32x32x16_bf16 v[112:127], v[164:167], v[220:223], v[112:127]
	v_cvt_pk_bf16_f32 v91, v94, v95
	v_exp_f32_e32 v104, v104
	v_exp_f32_e32 v105, v105
	v_add_f32_e32 v245, v245, v104
	v_mfma_f32_32x32x16_bf16 v[0:15], v[96:99], v[176:179], v[0:15]
	v_add_f32_e32 v245, v245, v105
	v_cvt_pk_bf16_f32 v104, v104, v105
	v_exp_f32_e32 v106, v106
	v_exp_f32_e32 v107, v107
	v_add_f32_e32 v245, v245, v106
	v_mfma_f32_32x32x16_bf16 v[128:143], v[164:167], v[228:231], v[128:143]
	v_add_f32_e32 v245, v245, v107
	v_cvt_pk_bf16_f32 v105, v106, v107
	v_exp_f32_e32 v108, v108
	v_exp_f32_e32 v109, v109
	v_add_f32_e32 v245, v245, v108
	s_waitcnt lgkmcnt(2)
	v_mfma_f32_32x32x16_bf16 v[48:63], v[88:91], v[172:175], v[48:63]
	v_add_f32_e32 v245, v245, v109
	v_cvt_pk_bf16_f32 v106, v108, v109
	v_exp_f32_e32 v110, v110
	v_exp_f32_e32 v111, v111
	s_waitcnt lgkmcnt(0)
	v_mfma_f32_32x32x16_bf16 v[32:47], v[88:91], v[180:183], v[32:47]
	v_add_f32_e32 v245, v245, v110
	v_add_f32_e32 v245, v245, v111
	v_cvt_pk_bf16_f32 v107, v110, v111
	ds_read_b64_tr_b16 v[168:169], v241 offset:61440
	ds_read_b64_tr_b16 v[170:171], v241 offset:62464
	ds_read_b64_tr_b16 v[176:177], v232 offset:61440
	ds_read_b64_tr_b16 v[178:179], v232 offset:62464
	v_mfma_f32_32x32x16_bf16 v[16:31], v[104:107], v[172:175], v[16:31]
	ds_read_b64_tr_b16 v[172:173], v241 offset:63488
	ds_read_b64_tr_b16 v[174:175], v241 offset:64512
	v_mfma_f32_32x32x16_bf16 v[0:15], v[104:107], v[180:183], v[0:15]
	ds_read_b64_tr_b16 v[180:181], v232 offset:63488
	ds_read_b64_tr_b16 v[182:183], v232 offset:64512
	s_waitcnt vmcnt(0)
	s_waitcnt lgkmcnt(0)
	s_barrier
	s_cmp_eq_u32 s28, 64
	s_cbranch_scc1 .Lmla_last
	s_and_b32 s12, s28, 1
	s_mul_i32 s13, s12, 0x6000
	v_add_u32_e32 v242, s13, v237
	v_lshl_add_u32 v241, s12, 14, v238
	v_add_u32_e32 v232, v241, v240
	v_add_u32_e32 v241, v241, v239
	ds_read_b128 v[144:147], v242
	ds_read_b128 v[148:151], v242 offset:1024
	ds_read_b128 v[152:155], v242 offset:2048
	ds_read_b128 v[156:159], v242 offset:3072
	ds_read_b128 v[160:163], v242 offset:4096
	ds_read_b128 v[164:167], v242 offset:5120
	v_exp_f32_e32 v112, v112
	v_exp_f32_e32 v113, v113
	v_add_f32_e32 v244, v244, v112
	v_add_f32_e32 v244, v244, v113
	v_cvt_pk_bf16_f32 v112, v112, v113
	v_exp_f32_e32 v114, v114
	v_exp_f32_e32 v115, v115
	v_add_f32_e32 v244, v244, v114
	v_add_f32_e32 v244, v244, v115
	v_cvt_pk_bf16_f32 v113, v114, v115
	v_exp_f32_e32 v116, v116
	v_exp_f32_e32 v117, v117
	v_add_f32_e32 v244, v244, v116
	v_add_f32_e32 v244, v244, v117
	v_cvt_pk_bf16_f32 v114, v116, v117
	v_exp_f32_e32 v118, v118
	v_exp_f32_e32 v119, v119
	v_add_f32_e32 v244, v244, v118
	v_add_f32_e32 v244, v244, v119
	v_cvt_pk_bf16_f32 v115, v118, v119
	s_nop 1
	v_mfma_f32_32x32x16_bf16 v[48:63], v[112:115], v[168:171], v[48:63]
	v_exp_f32_e32 v128, v128
	v_exp_f32_e32 v129, v129
	v_add_f32_e32 v245, v245, v128
	v_mfma_f32_32x32x16_bf16 v[32:47], v[112:115], v[176:179], v[32:47]
	v_add_f32_e32 v245, v245, v129
	v_cvt_pk_bf16_f32 v128, v128, v129
	v_exp_f32_e32 v130, v130
	s_waitcnt lgkmcnt(5)
	v_mfma_f32_32x32x16_bf16 v[80:95], v[144:147], v[184:187], v[64:79]
	v_exp_f32_e32 v131, v131
	v_add_f32_e32 v245, v245, v130
	v_add_f32_e32 v245, v245, v131
	v_mfma_f32_32x32x16_bf16 v[96:111], v[144:147], v[200:203], v[64:79]
	ds_read_b128 v[144:147], v242 offset:6144
	v_cvt_pk_bf16_f32 v129, v130, v131
	v_exp_f32_e32 v132, v132
	v_exp_f32_e32 v133, v133
	s_waitcnt lgkmcnt(5)
	v_mfma_f32_32x32x16_bf16 v[80:95], v[148:151], v[188:191], v[80:95]
	v_add_f32_e32 v245, v245, v132
	v_add_f32_e32 v245, v245, v133
	v_cvt_pk_bf16_f32 v130, v132, v133
	v_exp_f32_e32 v134, v134
	v_mfma_f32_32x32x16_bf16 v[96:111], v[148:151], v[204:207], v[96:111]
	ds_read_b128 v[148:151], v242 offset:7168
	v_exp_f32_e32 v135, v135
	v_add_f32_e32 v245, v245, v134
	v_add_f32_e32 v245, v245, v135
	v_cvt_pk_bf16_f32 v131, v134, v135
	s_waitcnt lgkmcnt(5)
	v_mfma_f32_32x32x16_bf16 v[80:95], v[152:155], v[192:195], v[80:95]
	v_exp_f32_e32 v120, v120
	v_exp_f32_e32 v121, v121
	v_add_f32_e32 v244, v244, v120
	v_mfma_f32_32x32x16_bf16 v[16:31], v[128:131], v[168:171], v[16:31]
	v_add_f32_e32 v244, v244, v121
	v_cvt_pk_bf16_f32 v120, v120, v121
	v_exp_f32_e32 v122, v122
	v_mfma_f32_32x32x16_bf16 v[0:15], v[128:131], v[176:179], v[0:15]
	v_exp_f32_e32 v123, v123
	v_add_f32_e32 v244, v244, v122
	v_add_f32_e32 v244, v244, v123
	v_mfma_f32_32x32x16_bf16 v[96:111], v[152:155], v[208:211], v[96:111]
	ds_read_b128 v[152:155], v242 offset:8192
	v_cvt_pk_bf16_f32 v121, v122, v123
	v_exp_f32_e32 v124, v124
	v_exp_f32_e32 v125, v125
	s_waitcnt lgkmcnt(5)
	v_mfma_f32_32x32x16_bf16 v[80:95], v[156:159], v[196:199], v[80:95]
	v_add_f32_e32 v244, v244, v124
	v_add_f32_e32 v244, v244, v125
	v_cvt_pk_bf16_f32 v122, v124, v125
	v_exp_f32_e32 v126, v126
	v_mfma_f32_32x32x16_bf16 v[96:111], v[156:159], v[212:215], v[96:111]
	ds_read_b128 v[156:159], v242 offset:9216
	v_exp_f32_e32 v127, v127
	v_add_f32_e32 v244, v244, v126
	v_add_f32_e32 v244, v244, v127
	v_cvt_pk_bf16_f32 v123, v126, v127
	s_waitcnt lgkmcnt(5)
	v_mfma_f32_32x32x16_bf16 v[80:95], v[160:163], v[216:219], v[80:95]
	v_exp_f32_e32 v136, v136
	v_exp_f32_e32 v137, v137
	v_add_f32_e32 v245, v245, v136
	v_mfma_f32_32x32x16_bf16 v[48:63], v[120:123], v[172:175], v[48:63]
	v_add_f32_e32 v245, v245, v137
	v_cvt_pk_bf16_f32 v136, v136, v137
	v_exp_f32_e32 v138, v138
	v_mfma_f32_32x32x16_bf16 v[32:47], v[120:123], v[180:183], v[32:47]
	v_exp_f32_e32 v139, v139
	v_add_f32_e32 v245, v245, v138
	v_add_f32_e32 v245, v245, v139
	v_mfma_f32_32x32x16_bf16 v[96:111], v[160:163], v[224:227], v[96:111]
	ds_read_b128 v[160:163], v242 offset:10240
	v_cvt_pk_bf16_f32 v137, v138, v139
	v_exp_f32_e32 v140, v140
	v_exp_f32_e32 v141, v141
	s_waitcnt lgkmcnt(5)
	v_mfma_f32_32x32x16_bf16 v[80:95], v[164:167], v[220:223], v[80:95]
	v_add_f32_e32 v245, v245, v140
	v_add_f32_e32 v245, v245, v141
	v_cvt_pk_bf16_f32 v138, v140, v141
	v_exp_f32_e32 v142, v142
	v_mfma_f32_32x32x16_bf16 v[96:111], v[164:167], v[228:231], v[96:111]
	ds_read_b128 v[164:167], v242 offset:11264
	v_exp_f32_e32 v143, v143
	v_add_f32_e32 v245, v245, v142
	v_add_f32_e32 v245, v245, v143
	v_cvt_pk_bf16_f32 v139, v142, v143
	ds_read_b64_tr_b16 v[168:169], v241 offset:49152
	ds_read_b64_tr_b16 v[170:171], v241 offset:50176
	ds_read_b64_tr_b16 v[176:177], v232 offset:49152
	ds_read_b64_tr_b16 v[178:179], v232 offset:50176
	v_mfma_f32_32x32x16_bf16 v[16:31], v[136:139], v[172:175], v[16:31]
	ds_read_b64_tr_b16 v[172:173], v241 offset:51200
	ds_read_b64_tr_b16 v[174:175], v241 offset:52224
	v_mfma_f32_32x32x16_bf16 v[0:15], v[136:139], v[180:183], v[0:15]
	ds_read_b64_tr_b16 v[180:181], v232 offset:51200
	ds_read_b64_tr_b16 v[182:183], v232 offset:52224
	s_branch .Lmla_tail
